# phase-0 pool-weight fold remapped to cut its L2 traffic 4x: workgroup = 128 columns x 16 pooled channels, 8 waves x 16 d (2 columns per lane, 16 loads in flight), partials combined through LDS
# baseline (speedup 1.0000x reference)
.LBB0_65:
	s_or_b64 exec, exec, s[20:21]
	v_mov_b32_e32 v3, 0
	s_mov_b32 s0, 0x20000
	v_cmp_gt_i32_e32 vcc, s0, v0
	s_waitcnt vmcnt(1)
	v_readlane_b32 s13, v247, 31
	v_readlane_b32 s12, v247, 30
	s_waitcnt vmcnt(0)
	v_readlane_b32 s15, v247, 33
	v_readlane_b32 s14, v247, 32
	s_and_saveexec_b64 s[16:17], vcc
	s_cbranch_execz .LBB0_70
	s_cmpk_lg_i32 s56, 0x100
	s_cbranch_scc1 .Lpf4_generic
	v_mbcnt_lo_u32_b32 v1, -1, 0
	v_mbcnt_hi_u32_b32 v1, -1, v1
	v_readlane_b32 s0, v246, 6
	s_lshr_b32 s1, s0, 6
	s_bfe_u32 s9, s0, 0x30003
	s_and_b32 s18, s0, 7
	v_lshrrev_b32_e32 v2, 2, v1
	v_and_b32_e32 v3, 3, v1
	v_lshlrev_b32_e32 v4, 9, v2
	v_lshl_add_u32 v4, v3, 4, v4
	s_lshl_b32 s30, s1, 16
	s_lshl_b32 s31, s9, 13
	s_add_i32 s30, s30, s31
	s_lshl_b32 s31, s94, 6
	s_add_i32 s30, s30, s31
	s_add_u32 s24, s12, s30
	s_addc_u32 s25, s13, 0
	global_load_dwordx4 v[14:17], v4, s[24:25]
	v_lshlrev_b32_e32 v5, 4, v3
	s_lshl_b32 s30, s1, 9
	s_add_i32 s30, s30, s31
	s_add_u32 s26, s14, s30
	s_addc_u32 s27, s15, 0
	global_load_dwordx4 v[18:21], v5, s[26:27]
	v_readlane_b32 s28, v247, 36
	v_readlane_b32 s29, v247, 37
	s_lshl_b32 s30, s1, 7
	s_lshl_b32 s31, s94, 4
	s_add_i32 s30, s30, s31
	s_lshl_b32 s30, s30, 12
	s_lshl_b32 s31, s18, 9
	s_add_i32 s30, s30, s31
	s_add_u32 s28, s28, s30
	s_addc_u32 s29, s29, 0
	v_lshlrev_b32_e32 v60, 3, v1
	s_nop 1
	global_load_dwordx2 v[64:65], v60, s[28:29]
	s_add_u32 s28, s28, 0x1000
	s_addc_u32 s29, s29, 0
	global_load_dwordx2 v[66:67], v60, s[28:29]
	s_add_u32 s28, s28, 0x1000
	s_addc_u32 s29, s29, 0
	global_load_dwordx2 v[68:69], v60, s[28:29]
	s_add_u32 s28, s28, 0x1000
	s_addc_u32 s29, s29, 0
	global_load_dwordx2 v[70:71], v60, s[28:29]
	s_add_u32 s28, s28, 0x1000
	s_addc_u32 s29, s29, 0
	global_load_dwordx2 v[72:73], v60, s[28:29]
	s_add_u32 s28, s28, 0x1000
	s_addc_u32 s29, s29, 0
	global_load_dwordx2 v[74:75], v60, s[28:29]
	s_add_u32 s28, s28, 0x1000
	s_addc_u32 s29, s29, 0
	global_load_dwordx2 v[76:77], v60, s[28:29]
	s_add_u32 s28, s28, 0x1000
	s_addc_u32 s29, s29, 0
	global_load_dwordx2 v[78:79], v60, s[28:29]
	s_add_u32 s28, s28, 0x1000
	s_addc_u32 s29, s29, 0
	global_load_dwordx2 v[80:81], v60, s[28:29]
	s_add_u32 s28, s28, 0x1000
	s_addc_u32 s29, s29, 0
	global_load_dwordx2 v[82:83], v60, s[28:29]
	s_add_u32 s28, s28, 0x1000
	s_addc_u32 s29, s29, 0
	global_load_dwordx2 v[84:85], v60, s[28:29]
	s_add_u32 s28, s28, 0x1000
	s_addc_u32 s29, s29, 0
	global_load_dwordx2 v[86:87], v60, s[28:29]
	s_add_u32 s28, s28, 0x1000
	s_addc_u32 s29, s29, 0
	global_load_dwordx2 v[88:89], v60, s[28:29]
	s_add_u32 s28, s28, 0x1000
	s_addc_u32 s29, s29, 0
	global_load_dwordx2 v[90:91], v60, s[28:29]
	s_add_u32 s28, s28, 0x1000
	s_addc_u32 s29, s29, 0
	global_load_dwordx2 v[92:93], v60, s[28:29]
	s_add_u32 s28, s28, 0x1000
	s_addc_u32 s29, s29, 0
	global_load_dwordx2 v[94:95], v60, s[28:29]
	s_add_u32 s28, s28, 0x1000
	s_addc_u32 s29, s29, 0
	s_waitcnt vmcnt(16)
	s_lshl_b32 s23, s94, 14
	v_lshlrev_b32_e32 v6, 8, v3
	v_lshl_add_u32 v6, v2, 2, v6
	v_add_u32_e32 v6, s23, v6
	ds_write_b32 v6, v14
	ds_write_b32 v6, v15 offset:64
	ds_write_b32 v6, v16 offset:128
	ds_write_b32 v6, v17 offset:192
	v_add_u32_e32 v7, s23, v5
	ds_write_b128 v7, v[18:21] offset:1024
	v_mov_b32_e32 v63, s23
	s_waitcnt lgkmcnt(0)
	v_mov_b32_e32 v10, 0
	v_mov_b32_e32 v11, 0
	v_mov_b32_e32 v12, 0
	v_mov_b32_e32 v13, 0
	v_mov_b32_e32 v14, 0
	v_mov_b32_e32 v15, 0
	v_mov_b32_e32 v16, 0
	v_mov_b32_e32 v17, 0
	v_mov_b32_e32 v18, 0
	v_mov_b32_e32 v19, 0
	v_mov_b32_e32 v20, 0
	v_mov_b32_e32 v21, 0
	v_mov_b32_e32 v22, 0
	v_mov_b32_e32 v23, 0
	v_mov_b32_e32 v24, 0
	v_mov_b32_e32 v25, 0
	v_mov_b32_e32 v26, 0
	v_mov_b32_e32 v27, 0
	v_mov_b32_e32 v28, 0
	v_mov_b32_e32 v29, 0
	v_mov_b32_e32 v30, 0
	v_mov_b32_e32 v31, 0
	v_mov_b32_e32 v32, 0
	v_mov_b32_e32 v33, 0
	v_mov_b32_e32 v34, 0
	v_mov_b32_e32 v35, 0
	v_mov_b32_e32 v36, 0
	v_mov_b32_e32 v37, 0
	v_mov_b32_e32 v38, 0
	v_mov_b32_e32 v39, 0
	v_mov_b32_e32 v40, 0
	v_mov_b32_e32 v41, 0
	ds_read_b128 v[128:131], v63 offset:0
	ds_read_b128 v[132:135], v63 offset:16
	ds_read_b128 v[136:139], v63 offset:32
	ds_read_b128 v[140:143], v63 offset:48
	ds_read_b128 v[144:147], v63 offset:64
	ds_read_b128 v[148:151], v63 offset:80
	ds_read_b128 v[152:155], v63 offset:96
	ds_read_b128 v[156:159], v63 offset:112
	ds_read_b128 v[160:163], v63 offset:128
	ds_read_b128 v[164:167], v63 offset:144
	ds_read_b128 v[168:171], v63 offset:160
	ds_read_b128 v[172:175], v63 offset:176
	ds_read_b128 v[176:179], v63 offset:192
	ds_read_b128 v[180:183], v63 offset:208
	ds_read_b128 v[184:187], v63 offset:224
	ds_read_b128 v[188:191], v63 offset:240
	ds_read_b128 v[124:127], v63 offset:1024
	s_waitcnt vmcnt(12)
	s_waitcnt lgkmcnt(0)
	v_mul_f32_e32 v232, v124, v64
	v_mul_f32_e32 v233, v124, v65
	v_fmac_f32_e32 v10, v128, v232
	v_fmac_f32_e32 v26, v128, v233
	v_fmac_f32_e32 v11, v129, v232
	v_fmac_f32_e32 v27, v129, v233
	v_fmac_f32_e32 v12, v130, v232
	v_fmac_f32_e32 v28, v130, v233
	v_fmac_f32_e32 v13, v131, v232
	v_fmac_f32_e32 v29, v131, v233
	v_fmac_f32_e32 v14, v132, v232
	v_fmac_f32_e32 v30, v132, v233
	v_fmac_f32_e32 v15, v133, v232
	v_fmac_f32_e32 v31, v133, v233
	v_fmac_f32_e32 v16, v134, v232
	v_fmac_f32_e32 v32, v134, v233
	v_fmac_f32_e32 v17, v135, v232
	v_fmac_f32_e32 v33, v135, v233
	v_fmac_f32_e32 v18, v136, v232
	v_fmac_f32_e32 v34, v136, v233
	v_fmac_f32_e32 v19, v137, v232
	v_fmac_f32_e32 v35, v137, v233
	v_fmac_f32_e32 v20, v138, v232
	v_fmac_f32_e32 v36, v138, v233
	v_fmac_f32_e32 v21, v139, v232
	v_fmac_f32_e32 v37, v139, v233
	v_fmac_f32_e32 v22, v140, v232
	v_fmac_f32_e32 v38, v140, v233
	v_fmac_f32_e32 v23, v141, v232
	v_fmac_f32_e32 v39, v141, v233
	v_fmac_f32_e32 v24, v142, v232
	v_fmac_f32_e32 v40, v142, v233
	v_fmac_f32_e32 v25, v143, v232
	v_fmac_f32_e32 v41, v143, v233
	v_mul_f32_e32 v232, v125, v66
	v_mul_f32_e32 v233, v125, v67
	v_fmac_f32_e32 v10, v144, v232
	v_fmac_f32_e32 v26, v144, v233
	v_fmac_f32_e32 v11, v145, v232
	v_fmac_f32_e32 v27, v145, v233
	v_fmac_f32_e32 v12, v146, v232
	v_fmac_f32_e32 v28, v146, v233
	v_fmac_f32_e32 v13, v147, v232
	v_fmac_f32_e32 v29, v147, v233
	v_fmac_f32_e32 v14, v148, v232
	v_fmac_f32_e32 v30, v148, v233
	v_fmac_f32_e32 v15, v149, v232
	v_fmac_f32_e32 v31, v149, v233
	v_fmac_f32_e32 v16, v150, v232
	v_fmac_f32_e32 v32, v150, v233
	v_fmac_f32_e32 v17, v151, v232
	v_fmac_f32_e32 v33, v151, v233
	v_fmac_f32_e32 v18, v152, v232
	v_fmac_f32_e32 v34, v152, v233
	v_fmac_f32_e32 v19, v153, v232
	v_fmac_f32_e32 v35, v153, v233
	v_fmac_f32_e32 v20, v154, v232
	v_fmac_f32_e32 v36, v154, v233
	v_fmac_f32_e32 v21, v155, v232
	v_fmac_f32_e32 v37, v155, v233
	v_fmac_f32_e32 v22, v156, v232
	v_fmac_f32_e32 v38, v156, v233
	v_fmac_f32_e32 v23, v157, v232
	v_fmac_f32_e32 v39, v157, v233
	v_fmac_f32_e32 v24, v158, v232
	v_fmac_f32_e32 v40, v158, v233
	v_fmac_f32_e32 v25, v159, v232
	v_fmac_f32_e32 v41, v159, v233
	v_mul_f32_e32 v232, v126, v68
	v_mul_f32_e32 v233, v126, v69
	v_fmac_f32_e32 v10, v160, v232
	v_fmac_f32_e32 v26, v160, v233
	v_fmac_f32_e32 v11, v161, v232
	v_fmac_f32_e32 v27, v161, v233
	v_fmac_f32_e32 v12, v162, v232
	v_fmac_f32_e32 v28, v162, v233
	v_fmac_f32_e32 v13, v163, v232
	v_fmac_f32_e32 v29, v163, v233
	v_fmac_f32_e32 v14, v164, v232
	v_fmac_f32_e32 v30, v164, v233
	v_fmac_f32_e32 v15, v165, v232
	v_fmac_f32_e32 v31, v165, v233
	v_fmac_f32_e32 v16, v166, v232
	v_fmac_f32_e32 v32, v166, v233
	v_fmac_f32_e32 v17, v167, v232
	v_fmac_f32_e32 v33, v167, v233
	v_fmac_f32_e32 v18, v168, v232
	v_fmac_f32_e32 v34, v168, v233
	v_fmac_f32_e32 v19, v169, v232
	v_fmac_f32_e32 v35, v169, v233
	v_fmac_f32_e32 v20, v170, v232
	v_fmac_f32_e32 v36, v170, v233
	v_fmac_f32_e32 v21, v171, v232
	v_fmac_f32_e32 v37, v171, v233
	v_fmac_f32_e32 v22, v172, v232
	v_fmac_f32_e32 v38, v172, v233
	v_fmac_f32_e32 v23, v173, v232
	v_fmac_f32_e32 v39, v173, v233
	v_fmac_f32_e32 v24, v174, v232
	v_fmac_f32_e32 v40, v174, v233
	v_fmac_f32_e32 v25, v175, v232
	v_fmac_f32_e32 v41, v175, v233
	v_mul_f32_e32 v232, v127, v70
	v_mul_f32_e32 v233, v127, v71
	v_fmac_f32_e32 v10, v176, v232
	v_fmac_f32_e32 v26, v176, v233
	v_fmac_f32_e32 v11, v177, v232
	v_fmac_f32_e32 v27, v177, v233
	v_fmac_f32_e32 v12, v178, v232
	v_fmac_f32_e32 v28, v178, v233
	v_fmac_f32_e32 v13, v179, v232
	v_fmac_f32_e32 v29, v179, v233
	v_fmac_f32_e32 v14, v180, v232
	v_fmac_f32_e32 v30, v180, v233
	v_fmac_f32_e32 v15, v181, v232
	v_fmac_f32_e32 v31, v181, v233
	v_fmac_f32_e32 v16, v182, v232
	v_fmac_f32_e32 v32, v182, v233
	v_fmac_f32_e32 v17, v183, v232
	v_fmac_f32_e32 v33, v183, v233
	v_fmac_f32_e32 v18, v184, v232
	v_fmac_f32_e32 v34, v184, v233
	v_fmac_f32_e32 v19, v185, v232
	v_fmac_f32_e32 v35, v185, v233
	v_fmac_f32_e32 v20, v186, v232
	v_fmac_f32_e32 v36, v186, v233
	v_fmac_f32_e32 v21, v187, v232
	v_fmac_f32_e32 v37, v187, v233
	v_fmac_f32_e32 v22, v188, v232
	v_fmac_f32_e32 v38, v188, v233
	v_fmac_f32_e32 v23, v189, v232
	v_fmac_f32_e32 v39, v189, v233
	v_fmac_f32_e32 v24, v190, v232
	v_fmac_f32_e32 v40, v190, v233
	v_fmac_f32_e32 v25, v191, v232
	v_fmac_f32_e32 v41, v191, v233
	ds_read_b128 v[128:131], v63 offset:256
	ds_read_b128 v[132:135], v63 offset:272
	ds_read_b128 v[136:139], v63 offset:288
	ds_read_b128 v[140:143], v63 offset:304
	ds_read_b128 v[144:147], v63 offset:320
	ds_read_b128 v[148:151], v63 offset:336
	ds_read_b128 v[152:155], v63 offset:352
	ds_read_b128 v[156:159], v63 offset:368
	ds_read_b128 v[160:163], v63 offset:384
	ds_read_b128 v[164:167], v63 offset:400
	ds_read_b128 v[168:171], v63 offset:416
	ds_read_b128 v[172:175], v63 offset:432
	ds_read_b128 v[176:179], v63 offset:448
	ds_read_b128 v[180:183], v63 offset:464
	ds_read_b128 v[184:187], v63 offset:480
	ds_read_b128 v[188:191], v63 offset:496
	ds_read_b128 v[124:127], v63 offset:1040
	s_waitcnt vmcnt(8)
	s_waitcnt lgkmcnt(0)
	v_mul_f32_e32 v232, v124, v72
	v_mul_f32_e32 v233, v124, v73
	v_fmac_f32_e32 v10, v128, v232
	v_fmac_f32_e32 v26, v128, v233
	v_fmac_f32_e32 v11, v129, v232
	v_fmac_f32_e32 v27, v129, v233
	v_fmac_f32_e32 v12, v130, v232
	v_fmac_f32_e32 v28, v130, v233
	v_fmac_f32_e32 v13, v131, v232
	v_fmac_f32_e32 v29, v131, v233
	v_fmac_f32_e32 v14, v132, v232
	v_fmac_f32_e32 v30, v132, v233
	v_fmac_f32_e32 v15, v133, v232
	v_fmac_f32_e32 v31, v133, v233
	v_fmac_f32_e32 v16, v134, v232
	v_fmac_f32_e32 v32, v134, v233
	v_fmac_f32_e32 v17, v135, v232
	v_fmac_f32_e32 v33, v135, v233
	v_fmac_f32_e32 v18, v136, v232
	v_fmac_f32_e32 v34, v136, v233
	v_fmac_f32_e32 v19, v137, v232
	v_fmac_f32_e32 v35, v137, v233
	v_fmac_f32_e32 v20, v138, v232
	v_fmac_f32_e32 v36, v138, v233
	v_fmac_f32_e32 v21, v139, v232
	v_fmac_f32_e32 v37, v139, v233
	v_fmac_f32_e32 v22, v140, v232
	v_fmac_f32_e32 v38, v140, v233
	v_fmac_f32_e32 v23, v141, v232
	v_fmac_f32_e32 v39, v141, v233
	v_fmac_f32_e32 v24, v142, v232
	v_fmac_f32_e32 v40, v142, v233
	v_fmac_f32_e32 v25, v143, v232
	v_fmac_f32_e32 v41, v143, v233
	v_mul_f32_e32 v232, v125, v74
	v_mul_f32_e32 v233, v125, v75
	v_fmac_f32_e32 v10, v144, v232
	v_fmac_f32_e32 v26, v144, v233
	v_fmac_f32_e32 v11, v145, v232
	v_fmac_f32_e32 v27, v145, v233
	v_fmac_f32_e32 v12, v146, v232
	v_fmac_f32_e32 v28, v146, v233
	v_fmac_f32_e32 v13, v147, v232
	v_fmac_f32_e32 v29, v147, v233
	v_fmac_f32_e32 v14, v148, v232
	v_fmac_f32_e32 v30, v148, v233
	v_fmac_f32_e32 v15, v149, v232
	v_fmac_f32_e32 v31, v149, v233
	v_fmac_f32_e32 v16, v150, v232
	v_fmac_f32_e32 v32, v150, v233
	v_fmac_f32_e32 v17, v151, v232
	v_fmac_f32_e32 v33, v151, v233
	v_fmac_f32_e32 v18, v152, v232
	v_fmac_f32_e32 v34, v152, v233
	v_fmac_f32_e32 v19, v153, v232
	v_fmac_f32_e32 v35, v153, v233
	v_fmac_f32_e32 v20, v154, v232
	v_fmac_f32_e32 v36, v154, v233
	v_fmac_f32_e32 v21, v155, v232
	v_fmac_f32_e32 v37, v155, v233
	v_fmac_f32_e32 v22, v156, v232
	v_fmac_f32_e32 v38, v156, v233
	v_fmac_f32_e32 v23, v157, v232
	v_fmac_f32_e32 v39, v157, v233
	v_fmac_f32_e32 v24, v158, v232
	v_fmac_f32_e32 v40, v158, v233
	v_fmac_f32_e32 v25, v159, v232
	v_fmac_f32_e32 v41, v159, v233
	v_mul_f32_e32 v232, v126, v76
	v_mul_f32_e32 v233, v126, v77
	v_fmac_f32_e32 v10, v160, v232
	v_fmac_f32_e32 v26, v160, v233
	v_fmac_f32_e32 v11, v161, v232
	v_fmac_f32_e32 v27, v161, v233
	v_fmac_f32_e32 v12, v162, v232
	v_fmac_f32_e32 v28, v162, v233
	v_fmac_f32_e32 v13, v163, v232
	v_fmac_f32_e32 v29, v163, v233
	v_fmac_f32_e32 v14, v164, v232
	v_fmac_f32_e32 v30, v164, v233
	v_fmac_f32_e32 v15, v165, v232
	v_fmac_f32_e32 v31, v165, v233
	v_fmac_f32_e32 v16, v166, v232
	v_fmac_f32_e32 v32, v166, v233
	v_fmac_f32_e32 v17, v167, v232
	v_fmac_f32_e32 v33, v167, v233
	v_fmac_f32_e32 v18, v168, v232
	v_fmac_f32_e32 v34, v168, v233
	v_fmac_f32_e32 v19, v169, v232
	v_fmac_f32_e32 v35, v169, v233
	v_fmac_f32_e32 v20, v170, v232
	v_fmac_f32_e32 v36, v170, v233
	v_fmac_f32_e32 v21, v171, v232
	v_fmac_f32_e32 v37, v171, v233
	v_fmac_f32_e32 v22, v172, v232
	v_fmac_f32_e32 v38, v172, v233
	v_fmac_f32_e32 v23, v173, v232
	v_fmac_f32_e32 v39, v173, v233
	v_fmac_f32_e32 v24, v174, v232
	v_fmac_f32_e32 v40, v174, v233
	v_fmac_f32_e32 v25, v175, v232
	v_fmac_f32_e32 v41, v175, v233
	v_mul_f32_e32 v232, v127, v78
	v_mul_f32_e32 v233, v127, v79
	v_fmac_f32_e32 v10, v176, v232
	v_fmac_f32_e32 v26, v176, v233
	v_fmac_f32_e32 v11, v177, v232
	v_fmac_f32_e32 v27, v177, v233
	v_fmac_f32_e32 v12, v178, v232
	v_fmac_f32_e32 v28, v178, v233
	v_fmac_f32_e32 v13, v179, v232
	v_fmac_f32_e32 v29, v179, v233
	v_fmac_f32_e32 v14, v180, v232
	v_fmac_f32_e32 v30, v180, v233
	v_fmac_f32_e32 v15, v181, v232
	v_fmac_f32_e32 v31, v181, v233
	v_fmac_f32_e32 v16, v182, v232
	v_fmac_f32_e32 v32, v182, v233
	v_fmac_f32_e32 v17, v183, v232
	v_fmac_f32_e32 v33, v183, v233
	v_fmac_f32_e32 v18, v184, v232
	v_fmac_f32_e32 v34, v184, v233
	v_fmac_f32_e32 v19, v185, v232
	v_fmac_f32_e32 v35, v185, v233
	v_fmac_f32_e32 v20, v186, v232
	v_fmac_f32_e32 v36, v186, v233
	v_fmac_f32_e32 v21, v187, v232
	v_fmac_f32_e32 v37, v187, v233
	v_fmac_f32_e32 v22, v188, v232
	v_fmac_f32_e32 v38, v188, v233
	v_fmac_f32_e32 v23, v189, v232
	v_fmac_f32_e32 v39, v189, v233
	v_fmac_f32_e32 v24, v190, v232
	v_fmac_f32_e32 v40, v190, v233
	v_fmac_f32_e32 v25, v191, v232
	v_fmac_f32_e32 v41, v191, v233
	ds_read_b128 v[128:131], v63 offset:512
	ds_read_b128 v[132:135], v63 offset:528
	ds_read_b128 v[136:139], v63 offset:544
	ds_read_b128 v[140:143], v63 offset:560
	ds_read_b128 v[144:147], v63 offset:576
	ds_read_b128 v[148:151], v63 offset:592
	ds_read_b128 v[152:155], v63 offset:608
	ds_read_b128 v[156:159], v63 offset:624
	ds_read_b128 v[160:163], v63 offset:640
	ds_read_b128 v[164:167], v63 offset:656
	ds_read_b128 v[168:171], v63 offset:672
	ds_read_b128 v[172:175], v63 offset:688
	ds_read_b128 v[176:179], v63 offset:704
	ds_read_b128 v[180:183], v63 offset:720
	ds_read_b128 v[184:187], v63 offset:736
	ds_read_b128 v[188:191], v63 offset:752
	ds_read_b128 v[124:127], v63 offset:1056
	s_waitcnt vmcnt(4)
	s_waitcnt lgkmcnt(0)
	v_mul_f32_e32 v232, v124, v80
	v_mul_f32_e32 v233, v124, v81
	v_fmac_f32_e32 v10, v128, v232
	v_fmac_f32_e32 v26, v128, v233
	v_fmac_f32_e32 v11, v129, v232
	v_fmac_f32_e32 v27, v129, v233
	v_fmac_f32_e32 v12, v130, v232
	v_fmac_f32_e32 v28, v130, v233
	v_fmac_f32_e32 v13, v131, v232
	v_fmac_f32_e32 v29, v131, v233
	v_fmac_f32_e32 v14, v132, v232
	v_fmac_f32_e32 v30, v132, v233
	v_fmac_f32_e32 v15, v133, v232
	v_fmac_f32_e32 v31, v133, v233
	v_fmac_f32_e32 v16, v134, v232
	v_fmac_f32_e32 v32, v134, v233
	v_fmac_f32_e32 v17, v135, v232
	v_fmac_f32_e32 v33, v135, v233
	v_fmac_f32_e32 v18, v136, v232
	v_fmac_f32_e32 v34, v136, v233
	v_fmac_f32_e32 v19, v137, v232
	v_fmac_f32_e32 v35, v137, v233
	v_fmac_f32_e32 v20, v138, v232
	v_fmac_f32_e32 v36, v138, v233
	v_fmac_f32_e32 v21, v139, v232
	v_fmac_f32_e32 v37, v139, v233
	v_fmac_f32_e32 v22, v140, v232
	v_fmac_f32_e32 v38, v140, v233
	v_fmac_f32_e32 v23, v141, v232
	v_fmac_f32_e32 v39, v141, v233
	v_fmac_f32_e32 v24, v142, v232
	v_fmac_f32_e32 v40, v142, v233
	v_fmac_f32_e32 v25, v143, v232
	v_fmac_f32_e32 v41, v143, v233
	v_mul_f32_e32 v232, v125, v82
	v_mul_f32_e32 v233, v125, v83
	v_fmac_f32_e32 v10, v144, v232
	v_fmac_f32_e32 v26, v144, v233
	v_fmac_f32_e32 v11, v145, v232
	v_fmac_f32_e32 v27, v145, v233
	v_fmac_f32_e32 v12, v146, v232
	v_fmac_f32_e32 v28, v146, v233
	v_fmac_f32_e32 v13, v147, v232
	v_fmac_f32_e32 v29, v147, v233
	v_fmac_f32_e32 v14, v148, v232
	v_fmac_f32_e32 v30, v148, v233
	v_fmac_f32_e32 v15, v149, v232
	v_fmac_f32_e32 v31, v149, v233
	v_fmac_f32_e32 v16, v150, v232
	v_fmac_f32_e32 v32, v150, v233
	v_fmac_f32_e32 v17, v151, v232
	v_fmac_f32_e32 v33, v151, v233
	v_fmac_f32_e32 v18, v152, v232
	v_fmac_f32_e32 v34, v152, v233
	v_fmac_f32_e32 v19, v153, v232
	v_fmac_f32_e32 v35, v153, v233
	v_fmac_f32_e32 v20, v154, v232
	v_fmac_f32_e32 v36, v154, v233
	v_fmac_f32_e32 v21, v155, v232
	v_fmac_f32_e32 v37, v155, v233
	v_fmac_f32_e32 v22, v156, v232
	v_fmac_f32_e32 v38, v156, v233
	v_fmac_f32_e32 v23, v157, v232
	v_fmac_f32_e32 v39, v157, v233
	v_fmac_f32_e32 v24, v158, v232
	v_fmac_f32_e32 v40, v158, v233
	v_fmac_f32_e32 v25, v159, v232
	v_fmac_f32_e32 v41, v159, v233
	v_mul_f32_e32 v232, v126, v84
	v_mul_f32_e32 v233, v126, v85
	v_fmac_f32_e32 v10, v160, v232
	v_fmac_f32_e32 v26, v160, v233
	v_fmac_f32_e32 v11, v161, v232
	v_fmac_f32_e32 v27, v161, v233
	v_fmac_f32_e32 v12, v162, v232
	v_fmac_f32_e32 v28, v162, v233
	v_fmac_f32_e32 v13, v163, v232
	v_fmac_f32_e32 v29, v163, v233
	v_fmac_f32_e32 v14, v164, v232
	v_fmac_f32_e32 v30, v164, v233
	v_fmac_f32_e32 v15, v165, v232
	v_fmac_f32_e32 v31, v165, v233
	v_fmac_f32_e32 v16, v166, v232
	v_fmac_f32_e32 v32, v166, v233
	v_fmac_f32_e32 v17, v167, v232
	v_fmac_f32_e32 v33, v167, v233
	v_fmac_f32_e32 v18, v168, v232
	v_fmac_f32_e32 v34, v168, v233
	v_fmac_f32_e32 v19, v169, v232
	v_fmac_f32_e32 v35, v169, v233
	v_fmac_f32_e32 v20, v170, v232
	v_fmac_f32_e32 v36, v170, v233
	v_fmac_f32_e32 v21, v171, v232
	v_fmac_f32_e32 v37, v171, v233
	v_fmac_f32_e32 v22, v172, v232
	v_fmac_f32_e32 v38, v172, v233
	v_fmac_f32_e32 v23, v173, v232
	v_fmac_f32_e32 v39, v173, v233
	v_fmac_f32_e32 v24, v174, v232
	v_fmac_f32_e32 v40, v174, v233
	v_fmac_f32_e32 v25, v175, v232
	v_fmac_f32_e32 v41, v175, v233
	v_mul_f32_e32 v232, v127, v86
	v_mul_f32_e32 v233, v127, v87
	v_fmac_f32_e32 v10, v176, v232
	v_fmac_f32_e32 v26, v176, v233
	v_fmac_f32_e32 v11, v177, v232
	v_fmac_f32_e32 v27, v177, v233
	v_fmac_f32_e32 v12, v178, v232
	v_fmac_f32_e32 v28, v178, v233
	v_fmac_f32_e32 v13, v179, v232
	v_fmac_f32_e32 v29, v179, v233
	v_fmac_f32_e32 v14, v180, v232
	v_fmac_f32_e32 v30, v180, v233
	v_fmac_f32_e32 v15, v181, v232
	v_fmac_f32_e32 v31, v181, v233
	v_fmac_f32_e32 v16, v182, v232
	v_fmac_f32_e32 v32, v182, v233
	v_fmac_f32_e32 v17, v183, v232
	v_fmac_f32_e32 v33, v183, v233
	v_fmac_f32_e32 v18, v184, v232
	v_fmac_f32_e32 v34, v184, v233
	v_fmac_f32_e32 v19, v185, v232
	v_fmac_f32_e32 v35, v185, v233
	v_fmac_f32_e32 v20, v186, v232
	v_fmac_f32_e32 v36, v186, v233
	v_fmac_f32_e32 v21, v187, v232
	v_fmac_f32_e32 v37, v187, v233
	v_fmac_f32_e32 v22, v188, v232
	v_fmac_f32_e32 v38, v188, v233
	v_fmac_f32_e32 v23, v189, v232
	v_fmac_f32_e32 v39, v189, v233
	v_fmac_f32_e32 v24, v190, v232
	v_fmac_f32_e32 v40, v190, v233
	v_fmac_f32_e32 v25, v191, v232
	v_fmac_f32_e32 v41, v191, v233
	ds_read_b128 v[128:131], v63 offset:768
	ds_read_b128 v[132:135], v63 offset:784
	ds_read_b128 v[136:139], v63 offset:800
	ds_read_b128 v[140:143], v63 offset:816
	ds_read_b128 v[144:147], v63 offset:832
	ds_read_b128 v[148:151], v63 offset:848
	ds_read_b128 v[152:155], v63 offset:864
	ds_read_b128 v[156:159], v63 offset:880
	ds_read_b128 v[160:163], v63 offset:896
	ds_read_b128 v[164:167], v63 offset:912
	ds_read_b128 v[168:171], v63 offset:928
	ds_read_b128 v[172:175], v63 offset:944
	ds_read_b128 v[176:179], v63 offset:960
	ds_read_b128 v[180:183], v63 offset:976
	ds_read_b128 v[184:187], v63 offset:992
	ds_read_b128 v[188:191], v63 offset:1008
	ds_read_b128 v[124:127], v63 offset:1072
	s_waitcnt vmcnt(0)
	s_waitcnt lgkmcnt(0)
	v_mul_f32_e32 v232, v124, v88
	v_mul_f32_e32 v233, v124, v89
	v_fmac_f32_e32 v10, v128, v232
	v_fmac_f32_e32 v26, v128, v233
	v_fmac_f32_e32 v11, v129, v232
	v_fmac_f32_e32 v27, v129, v233
	v_fmac_f32_e32 v12, v130, v232
	v_fmac_f32_e32 v28, v130, v233
	v_fmac_f32_e32 v13, v131, v232
	v_fmac_f32_e32 v29, v131, v233
	v_fmac_f32_e32 v14, v132, v232
	v_fmac_f32_e32 v30, v132, v233
	v_fmac_f32_e32 v15, v133, v232
	v_fmac_f32_e32 v31, v133, v233
	v_fmac_f32_e32 v16, v134, v232
	v_fmac_f32_e32 v32, v134, v233
	v_fmac_f32_e32 v17, v135, v232
	v_fmac_f32_e32 v33, v135, v233
	v_fmac_f32_e32 v18, v136, v232
	v_fmac_f32_e32 v34, v136, v233
	v_fmac_f32_e32 v19, v137, v232
	v_fmac_f32_e32 v35, v137, v233
	v_fmac_f32_e32 v20, v138, v232
	v_fmac_f32_e32 v36, v138, v233
	v_fmac_f32_e32 v21, v139, v232
	v_fmac_f32_e32 v37, v139, v233
	v_fmac_f32_e32 v22, v140, v232
	v_fmac_f32_e32 v38, v140, v233
	v_fmac_f32_e32 v23, v141, v232
	v_fmac_f32_e32 v39, v141, v233
	v_fmac_f32_e32 v24, v142, v232
	v_fmac_f32_e32 v40, v142, v233
	v_fmac_f32_e32 v25, v143, v232
	v_fmac_f32_e32 v41, v143, v233
	v_mul_f32_e32 v232, v125, v90
	v_mul_f32_e32 v233, v125, v91
	v_fmac_f32_e32 v10, v144, v232
	v_fmac_f32_e32 v26, v144, v233
	v_fmac_f32_e32 v11, v145, v232
	v_fmac_f32_e32 v27, v145, v233
	v_fmac_f32_e32 v12, v146, v232
	v_fmac_f32_e32 v28, v146, v233
	v_fmac_f32_e32 v13, v147, v232
	v_fmac_f32_e32 v29, v147, v233
	v_fmac_f32_e32 v14, v148, v232
	v_fmac_f32_e32 v30, v148, v233
	v_fmac_f32_e32 v15, v149, v232
	v_fmac_f32_e32 v31, v149, v233
	v_fmac_f32_e32 v16, v150, v232
	v_fmac_f32_e32 v32, v150, v233
	v_fmac_f32_e32 v17, v151, v232
	v_fmac_f32_e32 v33, v151, v233
	v_fmac_f32_e32 v18, v152, v232
	v_fmac_f32_e32 v34, v152, v233
	v_fmac_f32_e32 v19, v153, v232
	v_fmac_f32_e32 v35, v153, v233
	v_fmac_f32_e32 v20, v154, v232
	v_fmac_f32_e32 v36, v154, v233
	v_fmac_f32_e32 v21, v155, v232
	v_fmac_f32_e32 v37, v155, v233
	v_fmac_f32_e32 v22, v156, v232
	v_fmac_f32_e32 v38, v156, v233
	v_fmac_f32_e32 v23, v157, v232
	v_fmac_f32_e32 v39, v157, v233
	v_fmac_f32_e32 v24, v158, v232
	v_fmac_f32_e32 v40, v158, v233
	v_fmac_f32_e32 v25, v159, v232
	v_fmac_f32_e32 v41, v159, v233
	v_mul_f32_e32 v232, v126, v92
	v_mul_f32_e32 v233, v126, v93
	v_fmac_f32_e32 v10, v160, v232
	v_fmac_f32_e32 v26, v160, v233
	v_fmac_f32_e32 v11, v161, v232
	v_fmac_f32_e32 v27, v161, v233
	v_fmac_f32_e32 v12, v162, v232
	v_fmac_f32_e32 v28, v162, v233
	v_fmac_f32_e32 v13, v163, v232
	v_fmac_f32_e32 v29, v163, v233
	v_fmac_f32_e32 v14, v164, v232
	v_fmac_f32_e32 v30, v164, v233
	v_fmac_f32_e32 v15, v165, v232
	v_fmac_f32_e32 v31, v165, v233
	v_fmac_f32_e32 v16, v166, v232
	v_fmac_f32_e32 v32, v166, v233
	v_fmac_f32_e32 v17, v167, v232
	v_fmac_f32_e32 v33, v167, v233
	v_fmac_f32_e32 v18, v168, v232
	v_fmac_f32_e32 v34, v168, v233
	v_fmac_f32_e32 v19, v169, v232
	v_fmac_f32_e32 v35, v169, v233
	v_fmac_f32_e32 v20, v170, v232
	v_fmac_f32_e32 v36, v170, v233
	v_fmac_f32_e32 v21, v171, v232
	v_fmac_f32_e32 v37, v171, v233
	v_fmac_f32_e32 v22, v172, v232
	v_fmac_f32_e32 v38, v172, v233
	v_fmac_f32_e32 v23, v173, v232
	v_fmac_f32_e32 v39, v173, v233
	v_fmac_f32_e32 v24, v174, v232
	v_fmac_f32_e32 v40, v174, v233
	v_fmac_f32_e32 v25, v175, v232
	v_fmac_f32_e32 v41, v175, v233
	v_mul_f32_e32 v232, v127, v94
	v_mul_f32_e32 v233, v127, v95
	v_fmac_f32_e32 v10, v176, v232
	v_fmac_f32_e32 v26, v176, v233
	v_fmac_f32_e32 v11, v177, v232
	v_fmac_f32_e32 v27, v177, v233
	v_fmac_f32_e32 v12, v178, v232
	v_fmac_f32_e32 v28, v178, v233
	v_fmac_f32_e32 v13, v179, v232
	v_fmac_f32_e32 v29, v179, v233
	v_fmac_f32_e32 v14, v180, v232
	v_fmac_f32_e32 v30, v180, v233
	v_fmac_f32_e32 v15, v181, v232
	v_fmac_f32_e32 v31, v181, v233
	v_fmac_f32_e32 v16, v182, v232
	v_fmac_f32_e32 v32, v182, v233
	v_fmac_f32_e32 v17, v183, v232
	v_fmac_f32_e32 v33, v183, v233
	v_fmac_f32_e32 v18, v184, v232
	v_fmac_f32_e32 v34, v184, v233
	v_fmac_f32_e32 v19, v185, v232
	v_fmac_f32_e32 v35, v185, v233
	v_fmac_f32_e32 v20, v186, v232
	v_fmac_f32_e32 v36, v186, v233
	v_fmac_f32_e32 v21, v187, v232
	v_fmac_f32_e32 v37, v187, v233
	v_fmac_f32_e32 v22, v188, v232
	v_fmac_f32_e32 v38, v188, v233
	v_fmac_f32_e32 v23, v189, v232
	v_fmac_f32_e32 v39, v189, v233
	v_fmac_f32_e32 v24, v190, v232
	v_fmac_f32_e32 v40, v190, v233
	v_fmac_f32_e32 v25, v191, v232
	v_fmac_f32_e32 v41, v191, v233
	s_waitcnt lgkmcnt(0)
	s_barrier
	s_lshl_b32 s30, s94, 13
	v_lshl_add_u32 v58, v1, 7, s30
	ds_write_b128 v58, v[10:13]
	ds_write_b128 v58, v[14:17] offset:16
	ds_write_b128 v58, v[18:21] offset:32
	ds_write_b128 v58, v[22:25] offset:48
	ds_write_b128 v58, v[26:29] offset:64
	ds_write_b128 v58, v[30:33] offset:80
	ds_write_b128 v58, v[34:37] offset:96
	ds_write_b128 v58, v[38:41] offset:112
	s_waitcnt lgkmcnt(0)
	s_barrier
	s_lshl_b32 s30, s94, 10
	v_lshl_add_u32 v58, v1, 4, s30
	ds_read_b128 v[192:195], v58
	ds_read_b128 v[196:199], v58 offset:8192
	ds_read_b128 v[200:203], v58 offset:16384
	ds_read_b128 v[204:207], v58 offset:24576
	ds_read_b128 v[208:211], v58 offset:32768
	ds_read_b128 v[212:215], v58 offset:40960
	ds_read_b128 v[216:219], v58 offset:49152
	ds_read_b128 v[220:223], v58 offset:57344
	s_waitcnt lgkmcnt(0)
	v_pk_add_f32 v[192:193], v[192:193], v[196:197]
	v_pk_add_f32 v[194:195], v[194:195], v[198:199]
	v_pk_add_f32 v[192:193], v[192:193], v[200:201]
	v_pk_add_f32 v[194:195], v[194:195], v[202:203]
	v_pk_add_f32 v[192:193], v[192:193], v[204:205]
	v_pk_add_f32 v[194:195], v[194:195], v[206:207]
	v_pk_add_f32 v[192:193], v[192:193], v[208:209]
	v_pk_add_f32 v[194:195], v[194:195], v[210:211]
	v_pk_add_f32 v[192:193], v[192:193], v[212:213]
	v_pk_add_f32 v[194:195], v[194:195], v[214:215]
	v_pk_add_f32 v[192:193], v[192:193], v[216:217]
	v_pk_add_f32 v[194:195], v[194:195], v[218:219]
	v_pk_add_f32 v[192:193], v[192:193], v[220:221]
	v_pk_add_f32 v[194:195], v[194:195], v[222:223]
	s_lshl_b32 s30, s18, 7
	s_lshl_b32 s31, s94, 4
	s_add_i32 s30, s30, s31
	v_add_u32_e32 v8, s30, v2
	v_lshlrev_b32_e32 v8, 11, v8
	v_lshl_add_u32 v8, v3, 3, v8
	s_lshl_b32 s30, s1, 7
	s_lshl_b32 s31, s9, 4
	s_add_i32 s30, s30, s31
	s_lshl_b32 s30, s30, 1
	s_add_u32 s34, s64, s30
	s_addc_u32 s35, s65, 0
	v_cvt_pk_bf16_f32 v6, v192, v193
	v_cvt_pk_bf16_f32 v7, v194, v195
	s_nop 1
	global_store_dwordx2 v8, v[6:7], s[34:35]
	s_waitcnt vmcnt(0) lgkmcnt(0)
	s_barrier
	s_branch .LBB0_70
